# NSA item pre-loop de-serialisation: compressed-branch gate + bias fetched at item start; compressed K/V staging loads all in flight at once
# speedup vs baseline: 1.0240x; 1.0047x over previous
.LBB0_303:
	s_and_b64 vcc, exec, s[40:41]
	s_cbranch_vccz .LBB0_298
	s_sub_i32 s45, s21, 0x100
	s_lshr_b32 s45, s45, 3
	s_sub_i32 s45, 63, s45
	s_lshl_b32 s45, s45, 3
	s_and_b32 s46, s21, 7
	s_or_b32 s45, s45, s46
	s_cmpk_lt_i32 s21, 0x100
	s_cselect_b32 s44, s21, s45
	v_mov_b32_e32 v118, v131
	s_lshl_b32 s22, s44, 2
	s_load_dwordx2 s[40:41], s[12:13], 0x170
	s_andn2_b32 s22, s22, 31
	v_ashrrev_i32_e32 v120, 3, v118
	s_sub_i32 s23, 0x7e0, s22
	v_and_b32_e32 v126, -8, v120
	v_bfe_u32 v121, v118, 2, 3
	v_add_u32_e32 v0, s23, v126
	s_lshl_b32 s24, s44, 10
	s_and_b32 s79, s44, 1
	v_and_b32_e32 v127, 3, v118
	v_or_b32_e32 v117, v0, v121
	s_and_b32 s24, s24, 0x1800
	v_lshl_or_b32 v129, s79, 2, v127
	v_add_u32_e32 v114, s24, v117
	s_waitcnt lgkmcnt(0)
	v_mov_b64_e32 v[2:3], s[40:41]
	v_bfe_u32 v135, v118, 5, 1
	v_mad_i64_i32 v[124:125], s[40:41], v114, s33, v[2:3]
	v_lshlrev_b32_e32 v0, 8, v129
	v_lshl_add_u64 v[2:3], v[124:125], 0, v[0:1]
	v_lshlrev_b32_e32 v122, 4, v135
	v_mov_b32_e32 v123, v1
	v_lshl_add_u64 v[2:3], v[2:3], 0, v[122:123]
	s_load_dwordx4 s[28:31], s[12:13], 0x198
	global_load_dwordx4 v[82:85], v[2:3], off
	global_load_dwordx4 v[86:89], v[2:3], off offset:32
	global_load_dwordx4 v[90:93], v[2:3], off offset:64
	global_load_dwordx4 v[94:97], v[2:3], off offset:96
	global_load_dwordx4 v[98:101], v[2:3], off offset:128
	global_load_dwordx4 v[102:105], v[2:3], off offset:160
	global_load_dwordx4 v[106:109], v[2:3], off offset:192
	global_load_dwordx4 v[110:113], v[2:3], off offset:224
	s_load_dwordx2 s[40:41], s[12:13], 0x20
	v_mul_u32_u24_e32 v10, 3, v129
	v_lshlrev_b32_e32 v12, 2, v10
	v_lshlrev_b32_e32 v10, 1, v10
	v_add_u32_e32 v10, 0x1400, v10
	v_mov_b32_e32 v11, 0
	v_lshl_add_u64 v[8:9], v[124:125], 0, v[10:11]
	global_load_ushort v208, v[8:9], off
	s_lshl_b32 s25, s44, 7
	s_and_b32 s82, s25, 0x380
	v_add_u32_e32 v0, 1, v129
	s_lshl_b32 s25, s82, 8
	v_cvt_f32_ubyte0_e32 v0, v0
	s_waitcnt lgkmcnt(0)
	global_load_dword v211, v12, s[40:41]
	s_add_u32 s28, s28, s25
	v_exp_f32_e64 v5, -v0
	s_addc_u32 s29, s29, 0
	s_add_u32 s30, s30, s25
	v_lshlrev_b32_e32 v0, 4, v118
	s_addc_u32 s31, s31, 0
	v_and_b32_e32 v0, 0xf0, v0
	v_and_b32_e32 v173, 31, v118
	v_ashrrev_i32_e32 v115, 31, v114
	v_lshlrev_b32_e32 v116, 7, v129
	v_lshlrev_b32_e32 v18, 3, v135
	v_lshlrev_b32_e32 v171, 3, v118
	v_lshl_add_u64 v[2:3], s[28:29], 0, v[0:1]
	v_add_u32_e32 v4, 16, v0
	v_lshl_add_u64 v[6:7], s[30:31], 0, v[0:1]
	s_mov_b32 s25, 0
	v_lshlrev_b32_e32 v8, 4, v118
	v_add_u32_e32 v8, 0x1000, v8
	v_add_u32_e32 v9, 0x2000, v8
	v_add_u32_e32 v10, 0x4000, v8
	v_add_u32_e32 v11, 0x6000, v8
	global_load_dwordx4 v[20:23], v8, s[28:29] offset:-4096
	global_load_dwordx4 v[24:27], v8, s[28:29]
	global_load_dwordx4 v[28:31], v9, s[28:29] offset:-4096
	global_load_dwordx4 v[32:35], v9, s[28:29]
	global_load_dwordx4 v[36:39], v10, s[28:29] offset:-4096
	global_load_dwordx4 v[40:43], v10, s[28:29]
	global_load_dwordx4 v[44:47], v11, s[28:29] offset:-4096
	global_load_dwordx4 v[48:51], v11, s[28:29]
	global_load_dwordx4 v[52:55], v8, s[30:31] offset:-4096
	global_load_dwordx4 v[56:59], v8, s[30:31]
	global_load_dwordx4 v[60:63], v9, s[30:31] offset:-4096
	global_load_dwordx4 v[64:67], v9, s[30:31]
	global_load_dwordx4 v[68:71], v10, s[30:31] offset:-4096
	global_load_dwordx4 v[72:75], v10, s[30:31]
	global_load_dwordx4 v[76:79], v11, s[30:31] offset:-4096
	global_load_dwordx4 v[12:15], v11, s[30:31]
	s_barrier
	v_lshrrev_b32_e32 v17, 4, v118
	v_mad_u32_u24 v16, v17, s36, v4
	s_waitcnt vmcnt(15)
	ds_write_b128 v16, v[20:23]
	s_waitcnt vmcnt(14)
	ds_write_b128 v16, v[24:27] offset:4352
	s_waitcnt vmcnt(13)
	ds_write_b128 v16, v[28:31] offset:8704
	s_waitcnt vmcnt(12)
	ds_write_b128 v16, v[32:35] offset:13056
	s_waitcnt vmcnt(11)
	ds_write_b128 v16, v[36:39] offset:17408
	s_waitcnt vmcnt(10)
	ds_write_b128 v16, v[40:43] offset:21760
	s_waitcnt vmcnt(9)
	ds_write_b128 v16, v[44:47] offset:26112
	s_waitcnt vmcnt(8)
	ds_write_b128 v16, v[48:51] offset:30464
	s_waitcnt vmcnt(7)
	ds_write_b128 v16, v[52:55] offset:34816
	s_waitcnt vmcnt(6)
	ds_write_b128 v16, v[56:59] offset:39168
	s_waitcnt vmcnt(5)
	ds_write_b128 v16, v[60:63] offset:43520
	s_waitcnt vmcnt(4)
	ds_write_b128 v16, v[64:67] offset:47872
	s_waitcnt vmcnt(3)
	ds_write_b128 v16, v[68:71] offset:52224
	s_waitcnt vmcnt(2)
	ds_write_b128 v16, v[72:75] offset:56576
	s_waitcnt vmcnt(1)
	ds_write_b128 v16, v[76:79] offset:60928
	s_waitcnt vmcnt(0)
	ds_write_b128 v16, v[12:15] offset:65280
	v_cmp_gt_i32_e32 vcc, 32, v118
	s_and_saveexec_b64 s[40:41], vcc
	v_lshl_add_u32 v0, v118, 2, 16
	v_add_u32_e32 v0, 0x11f80, v0
	ds_write_b32 v0, v1
	s_or_b64 exec, exec, s[40:41]
	v_and_b32_e32 v3, 64, v160
	v_xor_b32_e32 v2, 32, v160
	v_add_u32_e32 v128, 64, v3
	v_cmp_lt_i32_e32 vcc, v2, v128
	s_lshl_b32 s28, s44, 2
	s_and_b32 s28, s28, 0xffffffe0
	v_lshlrev_b32_e32 v0, 6, v135
	v_cndmask_b32_e32 v2, v160, v2, vcc
	v_lshlrev_b32_e32 v172, 2, v2
	v_add_u32_e32 v2, v121, v126
	v_subrev_u32_e32 v2, s28, v2
	v_sub_u32_e32 v2, v2, v0
	v_add_u32_e32 v19, 0x7e0, v2
	v_mul_u32_u24_e32 v2, 0x110, v173
	v_mul_f32_e32 v119, 0x3fb8aa3b, v5
	s_mov_b32 s25, 0
	v_add3_u32 v20, v2, v122, 16
	v_mov_b32_e32 v139, 0xf149f2ca
	v_mov_b32_e32 v22, 0
	s_movk_i32 s28, 0x9e
	s_movk_i32 s29, 0xae
	s_movk_i32 s30, 0xbe
	s_movk_i32 s31, 0xce
	s_movk_i32 s34, 0x11e
	s_movk_i32 s94, 0x12e
	s_movk_i32 s95, 0x13e
	s_movk_i32 s73, 0x14e
	s_movk_i32 s89, 0x1ae
	s_movk_i32 s1, 0x1be
	s_waitcnt lgkmcnt(0)
	s_barrier
.LBB0_309:
	v_add_u32_e32 v23, s25, v20
	ds_read_b128 v[2:5], v23
	ds_read_b128 v[24:27], v23 offset:32
	v_cvt_f32_i32_e32 v28, v19
	v_cmp_lt_i32_e32 vcc, 30, v19
	v_cmp_lt_i32_e64 s[40:41], 46, v19
	v_cmp_lt_i32_e64 s[42:43], 62, v19
	v_cmp_lt_i32_e64 s[44:45], s0, v19
	v_cmp_lt_i32_e64 s[68:69], s80, v19
	v_cmp_lt_i32_e64 s[46:47], s28, v19
	s_waitcnt lgkmcnt(1)
	v_mfma_f32_32x32x16_bf16 v[2:17], v[2:5], v[82:85], 0
	v_cmp_lt_i32_e64 s[48:49], s29, v19
	v_cmp_lt_i32_e64 s[50:51], s30, v19
	v_cmp_lt_i32_e64 s[52:53], s31, v19
	v_cmp_lt_i32_e64 s[54:55], s34, v19
	v_cmp_lt_i32_e64 s[56:57], s94, v19
	v_cmp_lt_i32_e64 s[58:59], s95, v19
	v_cmp_lt_i32_e64 s[60:61], s73, v19
	s_waitcnt lgkmcnt(0)
	v_mfma_f32_32x32x16_bf16 v[2:17], v[24:27], v[86:89], v[2:17]
	ds_read_b128 v[24:27], v23 offset:64
	v_cmp_lt_i32_e64 s[62:63], s3, v19
	v_cmp_lt_i32_e64 s[64:65], s89, v19
	v_cmp_lt_i32_e64 s[66:67], s1, v19
	v_mov_b32_e32 v21, v22
	v_mov_b32_e32 v22, v139
	s_addk_i32 s25, 0x2200
	v_add_u32_e32 v19, 0xfffffe00, v19
	s_waitcnt lgkmcnt(0)
	v_mfma_f32_32x32x16_bf16 v[2:17], v[24:27], v[90:93], v[2:17]
	ds_read_b128 v[24:27], v23 offset:96
	s_cmpk_lg_u32 s25, 0x8800
	s_waitcnt lgkmcnt(0)
	v_mfma_f32_32x32x16_bf16 v[2:17], v[24:27], v[94:97], v[2:17]
	ds_read_b128 v[24:27], v23 offset:128
	s_waitcnt lgkmcnt(0)
	v_mfma_f32_32x32x16_bf16 v[2:17], v[24:27], v[98:101], v[2:17]
	ds_read_b128 v[24:27], v23 offset:160
	s_waitcnt lgkmcnt(0)
	v_mfma_f32_32x32x16_bf16 v[2:17], v[24:27], v[102:105], v[2:17]
	ds_read_b128 v[24:27], v23 offset:192
	s_waitcnt lgkmcnt(0)
	v_mfma_f32_32x32x16_bf16 v[2:17], v[24:27], v[106:109], v[2:17]
	ds_read_b128 v[24:27], v23 offset:224
	v_add_f32_e32 v23, 0xc1780000, v28
	v_mul_f32_e64 v23, v23, -v119
	s_waitcnt lgkmcnt(0)
	v_mfma_f32_32x32x16_bf16 v[2:17], v[24:27], v[110:113], v[2:17]
	s_nop 11
	v_fmamk_f32 v2, v2, 0x3e0293ee, v23
	v_fmamk_f32 v3, v3, 0x3e0293ee, v23
	v_fmamk_f32 v4, v4, 0x3e0293ee, v23
	v_fmamk_f32 v5, v5, 0x3e0293ee, v23
	v_fmamk_f32 v6, v6, 0x3e0293ee, v23
	v_fmamk_f32 v7, v7, 0x3e0293ee, v23
	v_fmamk_f32 v8, v8, 0x3e0293ee, v23
	v_fmamk_f32 v9, v9, 0x3e0293ee, v23
	v_fmamk_f32 v10, v10, 0x3e0293ee, v23
	v_fmamk_f32 v11, v11, 0x3e0293ee, v23
	v_fmamk_f32 v12, v12, 0x3e0293ee, v23
	v_fmamk_f32 v13, v13, 0x3e0293ee, v23
	v_fmamk_f32 v14, v14, 0x3e0293ee, v23
	v_fmamk_f32 v15, v15, 0x3e0293ee, v23
	v_fmamk_f32 v16, v16, 0x3e0293ee, v23
	v_fmac_f32_e32 v23, 0x3e0293ee, v17
	v_fmac_f32_e32 v2, 0, v119
	v_fmac_f32_e32 v3, 0x41800000, v119
	v_fmac_f32_e32 v4, 0x42000000, v119
	v_fmac_f32_e32 v5, 0x42400000, v119
	v_fmac_f32_e32 v23, 0x43d80000, v119
	v_cndmask_b32_e32 v2, v162, v2, vcc
	v_cndmask_b32_e64 v3, v162, v3, s[40:41]
	v_fmac_f32_e32 v6, 0x43000000, v119
	v_fmac_f32_e32 v7, 0x43100000, v119
	v_cndmask_b32_e64 v4, v162, v4, s[42:43]
	v_cndmask_b32_e64 v5, v162, v5, s[44:45]
	v_cndmask_b32_e64 v17, v162, v23, s[68:69]
	v_max3_f32 v23, v2, s88, v3
	v_fmac_f32_e32 v8, 0x43200000, v119
	v_fmac_f32_e32 v9, 0x43300000, v119
	v_cndmask_b32_e64 v6, v162, v6, s[46:47]
	v_cndmask_b32_e64 v7, v162, v7, s[48:49]
	v_max3_f32 v23, v23, v4, v5
	v_fmac_f32_e32 v10, 0x43800000, v119
	v_fmac_f32_e32 v11, 0x43880000, v119
	v_cndmask_b32_e64 v8, v162, v8, s[50:51]
	v_cndmask_b32_e64 v9, v162, v9, s[52:53]
	v_max3_f32 v23, v23, v6, v7
	v_fmac_f32_e32 v12, 0x43900000, v119
	v_fmac_f32_e32 v13, 0x43980000, v119
	v_cndmask_b32_e64 v10, v162, v10, s[54:55]
	v_cndmask_b32_e64 v11, v162, v11, s[56:57]
	v_max3_f32 v23, v23, v8, v9
	v_fmac_f32_e32 v14, 0x43c00000, v119
	v_fmac_f32_e32 v15, 0x43c80000, v119
	v_cndmask_b32_e64 v12, v162, v12, s[58:59]
	v_cndmask_b32_e64 v13, v162, v13, s[60:61]
	v_max3_f32 v23, v23, v10, v11
	v_fmac_f32_e32 v16, 0x43d00000, v119
	v_cndmask_b32_e64 v14, v162, v14, s[62:63]
	v_cndmask_b32_e64 v15, v162, v15, s[64:65]
	v_max3_f32 v23, v23, v12, v13
	v_cndmask_b32_e64 v16, v162, v16, s[66:67]
	v_max3_f32 v23, v23, v14, v15
	v_max3_f32 v23, v23, v16, v17
	ds_bpermute_b32 v24, v172, v23
	v_cmp_lt_f32_e32 vcc, s35, v2
	v_cmp_lt_f32_e64 s[40:41], s35, v3
	v_cmp_lt_f32_e64 s[42:43], s35, v4
	v_cmp_lt_f32_e64 s[44:45], s35, v5
	s_waitcnt lgkmcnt(0)
	v_max3_f32 v139, v22, v23, v24
	v_sub_f32_e32 v2, v2, v139
	v_sub_f32_e32 v3, v3, v139
	v_exp_f32_e32 v2, v2
	v_sub_f32_e32 v4, v4, v139
	v_exp_f32_e32 v3, v3
	v_sub_f32_e32 v5, v5, v139
	v_exp_f32_e32 v4, v4
	v_cmp_lt_f32_e64 s[46:47], s35, v6
	v_sub_f32_e32 v6, v6, v139
	v_exp_f32_e32 v5, v5
	v_cmp_lt_f32_e64 s[48:49], s35, v7
	v_sub_f32_e32 v7, v7, v139
	v_exp_f32_e32 v6, v6
	v_add_f32_e32 v2, 0, v2
	v_cmp_lt_f32_e64 s[50:51], s35, v8
	v_sub_f32_e32 v8, v8, v139
	v_exp_f32_e32 v7, v7
	v_cndmask_b32_e64 v3, 0, v3, s[40:41]
	v_cndmask_b32_e32 v2, 0, v2, vcc
	v_cmp_lt_f32_e64 s[52:53], s35, v9
	v_sub_f32_e32 v9, v9, v139
	v_exp_f32_e32 v8, v8
	v_cndmask_b32_e64 v4, 0, v4, s[42:43]
	v_add_f32_e32 v2, v3, v2
	v_cmp_lt_f32_e64 s[54:55], s35, v10
	v_sub_f32_e32 v10, v10, v139
	v_exp_f32_e32 v9, v9
	v_cndmask_b32_e64 v5, 0, v5, s[44:45]
	v_add_f32_e32 v2, v4, v2
	v_cmp_lt_f32_e64 s[56:57], s35, v11
	v_sub_f32_e32 v11, v11, v139
	v_exp_f32_e32 v10, v10
	v_cndmask_b32_e64 v6, 0, v6, s[46:47]
	v_add_f32_e32 v2, v5, v2
	v_cmp_lt_f32_e64 s[58:59], s35, v12
	v_sub_f32_e32 v12, v12, v139
	v_exp_f32_e32 v11, v11
	v_cndmask_b32_e64 v7, 0, v7, s[48:49]
	v_add_f32_e32 v2, v6, v2
	v_cmp_lt_f32_e64 s[60:61], s35, v13
	v_sub_f32_e32 v13, v13, v139
	v_exp_f32_e32 v12, v12
	v_cndmask_b32_e64 v8, 0, v8, s[50:51]
	v_add_f32_e32 v2, v7, v2
	v_cmp_lt_f32_e64 s[62:63], s35, v14
	v_sub_f32_e32 v14, v14, v139
	v_exp_f32_e32 v13, v13
	v_cndmask_b32_e64 v9, 0, v9, s[52:53]
	v_add_f32_e32 v2, v8, v2
	v_cmp_lt_f32_e64 s[64:65], s35, v15
	v_sub_f32_e32 v15, v15, v139
	v_exp_f32_e32 v14, v14
	v_cndmask_b32_e64 v10, 0, v10, s[54:55]
	v_add_f32_e32 v2, v9, v2
	v_cmp_lt_f32_e64 s[66:67], s35, v16
	v_sub_f32_e32 v16, v16, v139
	v_exp_f32_e32 v15, v15
	v_cndmask_b32_e64 v11, 0, v11, s[56:57]
	v_add_f32_e32 v2, v10, v2
	v_cmp_lt_f32_e64 s[68:69], s35, v17
	v_sub_f32_e32 v17, v17, v139
	v_exp_f32_e32 v16, v16
	v_cndmask_b32_e64 v12, 0, v12, s[58:59]
	v_add_f32_e32 v2, v11, v2
	v_exp_f32_e32 v17, v17
	v_cndmask_b32_e64 v13, 0, v13, s[60:61]
	v_add_f32_e32 v2, v12, v2
	v_sub_f32_e32 v22, v22, v139
	v_cndmask_b32_e64 v14, 0, v14, s[62:63]
	v_add_f32_e32 v2, v13, v2
	v_exp_f32_e32 v23, v22
	v_cndmask_b32_e64 v15, 0, v15, s[64:65]
	v_add_f32_e32 v2, v14, v2
	v_cndmask_b32_e64 v16, 0, v16, s[66:67]
	v_add_f32_e32 v2, v15, v2
	v_cndmask_b32_e64 v17, 0, v17, s[68:69]
	v_add_f32_e32 v2, v16, v2
	v_add_f32_e32 v22, v17, v2
	v_fmac_f32_e32 v22, v21, v23
	s_cbranch_scc1 .LBB0_309
	v_add_u32_e32 v145, 16, v122
	v_mad_u32_u24 v149, v173, s36, v145
	ds_read_b128 v[2:5], v149
	ds_read_b128 v[24:27], v149 offset:32
	v_sub_u32_e32 v20, v117, v0
	v_cvt_f32_i32_e32 v21, v20
	ds_bpermute_b32 v19, v172, v22
	s_waitcnt lgkmcnt(2)
	v_mfma_f32_32x32x16_bf16 v[2:17], v[2:5], v[82:85], 0
	v_sub_u32_e32 v66, v145, v18
	v_add_f32_e32 v21, 0xc1780000, v21
	v_fma_f32 v21, v21, -v119, -v139
	s_waitcnt lgkmcnt(0)
	v_add_f32_e32 v18, v22, v19
	v_rcp_f32_e32 v19, v18
	v_cmp_lt_f32_e32 vcc, 0, v18
	s_movk_i32 s25, 0x4e
	v_mfma_f32_32x32x16_bf16 v[2:17], v[24:27], v[86:89], v[2:17]
	ds_read_b128 v[24:27], v149 offset:64
	ds_read_b128 v[28:31], v149 offset:96
	v_cndmask_b32_e32 v123, 0, v19, vcc
	v_cmp_lt_i32_e32 vcc, 30, v20
	s_waitcnt lgkmcnt(1)
	v_mfma_f32_32x32x16_bf16 v[2:17], v[24:27], v[90:93], v[2:17]
	s_waitcnt lgkmcnt(0)
	v_mfma_f32_32x32x16_bf16 v[2:17], v[28:31], v[94:97], v[2:17]
	ds_read_b128 v[24:27], v149 offset:128
	ds_read_b128 v[28:31], v149 offset:160
	s_waitcnt lgkmcnt(1)
	v_mfma_f32_32x32x16_bf16 v[2:17], v[24:27], v[98:101], v[2:17]
	ds_read_b128 v[24:27], v149 offset:192
	s_waitcnt lgkmcnt(1)
	v_mfma_f32_32x32x16_bf16 v[2:17], v[28:31], v[102:105], v[2:17]
	ds_read_b128 v[28:31], v149 offset:224
	s_waitcnt lgkmcnt(1)
	v_mfma_f32_32x32x16_bf16 v[2:17], v[24:27], v[106:109], v[2:17]
	s_waitcnt lgkmcnt(0)
	v_mfma_f32_32x32x16_bf16 v[2:17], v[28:31], v[110:113], v[2:17]
	s_nop 11
	v_fmamk_f32 v2, v2, 0x3e0293ee, v21
	v_fmamk_f32 v3, v3, 0x3e0293ee, v21
	v_fmac_f32_e32 v2, 0, v119
	v_fmamk_f32 v4, v4, 0x3e0293ee, v21
	v_fmac_f32_e32 v3, 0x41800000, v119
	v_exp_f32_e32 v2, v2
	v_fmamk_f32 v5, v5, 0x3e0293ee, v21
	v_fmac_f32_e32 v4, 0x42000000, v119
	v_exp_f32_e32 v3, v3
	v_fmamk_f32 v6, v6, 0x3e0293ee, v21
	v_fmac_f32_e32 v5, 0x42400000, v119
	v_exp_f32_e32 v4, v4
	v_fmamk_f32 v7, v7, 0x3e0293ee, v21
	v_fmac_f32_e32 v6, 0x43000000, v119
	v_exp_f32_e32 v5, v5
	v_fmamk_f32 v8, v8, 0x3e0293ee, v21
	v_fmac_f32_e32 v7, 0x43100000, v119
	v_exp_f32_e32 v6, v6
	v_mul_f32_e32 v2, v123, v2
	v_fmamk_f32 v9, v9, 0x3e0293ee, v21
	v_fmac_f32_e32 v8, 0x43200000, v119
	v_exp_f32_e32 v7, v7
	v_mul_f32_e32 v3, v123, v3
	v_cndmask_b32_e32 v18, 0, v2, vcc
	v_cmp_lt_i32_e32 vcc, 46, v20
	v_fmamk_f32 v10, v10, 0x3e0293ee, v21
	v_fmac_f32_e32 v9, 0x43300000, v119
	v_exp_f32_e32 v8, v8
	v_mul_f32_e32 v4, v123, v4
	v_cndmask_b32_e32 v19, 0, v3, vcc
	v_cmp_lt_i32_e32 vcc, 62, v20
	v_fmamk_f32 v11, v11, 0x3e0293ee, v21
	v_fmac_f32_e32 v10, 0x43800000, v119
	v_exp_f32_e32 v9, v9
	v_mul_f32_e32 v5, v123, v5
	v_cndmask_b32_e32 v22, 0, v4, vcc
	v_cmp_lt_i32_e32 vcc, s25, v20
	v_fmac_f32_e32 v11, 0x43880000, v119
	v_exp_f32_e32 v10, v10
	v_mul_f32_e32 v6, v123, v6
	v_cndmask_b32_e32 v23, 0, v5, vcc
	v_cmp_lt_i32_e32 vcc, s28, v20
	v_exp_f32_e32 v11, v11
	v_mul_f32_e32 v7, v123, v7
	v_cndmask_b32_e32 v24, 0, v6, vcc
	v_cmp_lt_i32_e32 vcc, s29, v20
	v_mul_f32_e32 v8, v123, v8
	v_mul_f32_e32 v9, v123, v9
	v_cndmask_b32_e32 v25, 0, v7, vcc
	v_cmp_lt_i32_e32 vcc, s30, v20
	v_mul_f32_e32 v10, v123, v10
	v_mul_f32_e32 v2, v123, v11
	v_cndmask_b32_e32 v26, 0, v8, vcc
	v_cmp_lt_i32_e32 vcc, s31, v20
	v_fmamk_f32 v3, v13, 0x3e0293ee, v21
	v_fmac_f32_e32 v3, 0x43980000, v119
	v_cndmask_b32_e32 v9, 0, v9, vcc
	v_cmp_lt_i32_e32 vcc, s34, v20
	v_exp_f32_e32 v3, v3
	v_mul_f32_e32 v5, 0.5, v9
	v_cndmask_b32_e32 v67, 0, v10, vcc
	v_cmp_lt_i32_e32 vcc, s94, v20
	ds_bpermute_b32 v5, v172, v5
	s_nop 0
	v_cndmask_b32_e32 v68, 0, v2, vcc
	v_fmamk_f32 v2, v12, 0x3e0293ee, v21
	v_fmac_f32_e32 v2, 0x43900000, v119
	v_exp_f32_e32 v2, v2
	v_cmp_lt_i32_e32 vcc, s95, v20
	v_mul_f32_e32 v2, v123, v2
	s_nop 0
	v_cndmask_b32_e32 v69, 0, v2, vcc
	v_mul_f32_e32 v2, v123, v3
	v_cmp_lt_i32_e32 vcc, s73, v20
	v_fmamk_f32 v3, v15, 0x3e0293ee, v21
	v_fmac_f32_e32 v3, 0x43c80000, v119
	v_cndmask_b32_e32 v70, 0, v2, vcc
	v_fmamk_f32 v2, v14, 0x3e0293ee, v21
	v_fmac_f32_e32 v2, 0x43c00000, v119
	v_exp_f32_e32 v2, v2
	v_exp_f32_e32 v3, v3
	v_cmp_lt_i32_e32 vcc, s3, v20
	v_mul_f32_e32 v2, v123, v2
	s_nop 0
	v_cndmask_b32_e32 v71, 0, v2, vcc
	v_mul_f32_e32 v2, v123, v3
	v_cmp_lt_i32_e32 vcc, s89, v20
	s_nop 1
	v_cndmask_b32_e32 v72, 0, v2, vcc
	v_fmamk_f32 v2, v16, 0x3e0293ee, v21
	v_fmac_f32_e32 v2, 0x43d00000, v119
	v_fmac_f32_e32 v21, 0x3e0293ee, v17
	v_exp_f32_e32 v2, v2
	v_fmac_f32_e32 v21, 0x43d80000, v119
	v_exp_f32_e32 v3, v21
	v_cmp_lt_i32_e32 vcc, s1, v20
	v_mul_f32_e32 v2, v123, v2
	s_nop 0
	v_cndmask_b32_e32 v73, 0, v2, vcc
	v_mul_f32_e32 v2, v123, v3
	v_cmp_lt_i32_e32 vcc, s80, v20
	v_add_f32_e32 v3, v18, v19
	v_add_f32_e32 v3, v22, v3
	v_cndmask_b32_e32 v74, 0, v2, vcc
	v_mul_f32_e32 v2, 0.5, v23
	ds_bpermute_b32 v2, v172, v2
	v_cmp_eq_u32_e32 vcc, 0, v135
	v_fmac_f32_e32 v3, 0.5, v23
	s_waitcnt lgkmcnt(0)
	v_cndmask_b32_e64 v4, v2, 0, vcc
	v_add_f32_e32 v138, v4, v3
	v_mul_f32_e32 v4, 0.5, v70
	ds_bpermute_b32 v4, v172, v4
	v_add_f32_e32 v3, v24, v25
	v_add_f32_e32 v3, v26, v3
	v_fmac_f32_e32 v3, 0.5, v9
	v_cndmask_b32_e32 v2, v5, v2, vcc
	v_add_f32_e32 v137, v2, v3
	s_waitcnt lgkmcnt(0)
	v_cndmask_b32_e32 v3, v4, v5, vcc
	v_mul_f32_e32 v5, 0.5, v74
	v_add_f32_e32 v2, v67, v68
	ds_bpermute_b32 v140, v172, v5
	v_add_f32_e32 v2, v69, v2
	v_fmac_f32_e32 v2, 0.5, v70
	v_add_f32_e32 v136, v3, v2
	v_add_f32_e32 v2, v71, v72
	v_add_f32_e32 v2, v73, v2
	v_fmac_f32_e32 v2, 0.5, v74
	s_waitcnt lgkmcnt(0)
	v_cndmask_b32_e32 v3, v140, v4, vcc
	v_add_f32_e32 v133, v3, v2
	v_mad_u32_u24 v10, v173, s36, v66
	v_add_u32_e32 v144, 0x8800, v10
	ds_read2_b64 v[2:5], v144 offset1:2
	v_mad_u32_u24 v75, v173, s36, v163
	v_add_u32_e32 v11, v66, v75
	v_cvt_pk_bf16_f32 v6, v18, v19
	v_cvt_pk_bf16_f32 v7, v22, v23
	v_cvt_pk_bf16_f32 v8, v24, v25
	v_cvt_pk_bf16_f32 v9, v26, v9
	v_add_u32_e32 v141, 0x8800, v11
	v_add_u32_e32 v142, 0xc800, v10
	s_waitcnt lgkmcnt(0)
	v_mfma_f32_32x32x16_bf16 v[50:65], v[2:5], v[6:9], 0
	ds_read2_b64 v[2:5], v141 offset1:2
	v_mad_u32_u24 v153, v173, s36, v164
	s_waitcnt lgkmcnt(0)
	v_mfma_f32_32x32x16_bf16 v[34:49], v[2:5], v[6:9], 0
	ds_read2_b64 v[2:5], v142 offset0:128 offset1:130
	s_waitcnt lgkmcnt(0)
	v_mfma_f32_32x32x16_bf16 v[18:33], v[2:5], v[6:9], 0
	v_add_u32_e32 v2, v66, v153
	v_add_u32_e32 v143, 0x8800, v2
	ds_read2_b64 v[2:5], v143 offset1:2
	s_waitcnt lgkmcnt(0)
	v_mfma_f32_32x32x16_bf16 v[2:17], v[2:5], v[6:9], 0
	v_cvt_pk_bf16_f32 v66, v67, v68
	v_cvt_pk_bf16_f32 v67, v69, v70
	v_cvt_pk_bf16_f32 v68, v71, v72
	v_cvt_pk_bf16_f32 v69, v73, v74
	ds_read2_b64 v[70:73], v144 offset0:4 offset1:6
	s_waitcnt lgkmcnt(0)
	v_mfma_f32_32x32x16_bf16 v[50:65], v[70:73], v[66:69], v[50:65]
	ds_read2_b64 v[70:73], v141 offset0:4 offset1:6
	s_waitcnt lgkmcnt(0)
	v_mfma_f32_32x32x16_bf16 v[34:49], v[70:73], v[66:69], v[34:49]
	ds_read2_b64 v[70:73], v142 offset0:132 offset1:134
	s_waitcnt lgkmcnt(0)
	v_mfma_f32_32x32x16_bf16 v[18:33], v[70:73], v[66:69], v[18:33]
	ds_read2_b64 v[70:73], v143 offset0:4 offset1:6
	s_waitcnt lgkmcnt(0)
	v_mfma_f32_32x32x16_bf16 v[2:17], v[70:73], v[66:69], v[2:17]
	v_add_u32_e32 v146, v145, v75
	ds_read_b128 v[66:69], v146
	ds_read_b128 v[174:177], v146 offset:32
	s_waitcnt lgkmcnt(1)
	v_mfma_f32_32x32x16_bf16 v[66:81], v[66:69], v[82:85], 0
	s_waitcnt lgkmcnt(0)
	v_mfma_f32_32x32x16_bf16 v[66:81], v[174:177], v[86:89], v[66:81]
	ds_read_b128 v[174:177], v146 offset:64
	s_waitcnt lgkmcnt(0)
	v_mfma_f32_32x32x16_bf16 v[66:81], v[174:177], v[90:93], v[66:81]
	ds_read_b128 v[174:177], v146 offset:96
	s_waitcnt lgkmcnt(0)
	v_mfma_f32_32x32x16_bf16 v[66:81], v[174:177], v[94:97], v[66:81]
	ds_read_b128 v[174:177], v146 offset:128
	s_waitcnt lgkmcnt(0)
	v_mfma_f32_32x32x16_bf16 v[66:81], v[174:177], v[98:101], v[66:81]
	ds_read_b128 v[174:177], v146 offset:160
	s_waitcnt lgkmcnt(0)
	v_mfma_f32_32x32x16_bf16 v[66:81], v[174:177], v[102:105], v[66:81]
	ds_read_b128 v[174:177], v146 offset:192
	s_waitcnt lgkmcnt(0)
	v_mfma_f32_32x32x16_bf16 v[66:81], v[174:177], v[106:109], v[66:81]
	ds_read_b128 v[174:177], v146 offset:224
	v_or_b32_e32 v146, 0x200, v0
	v_sub_u32_e32 v146, v117, v146
	v_cvt_f32_i32_e32 v147, v146
	v_cmp_lt_i32_e64 s[40:41], 30, v146
	v_add_f32_e32 v147, 0xc1780000, v147
	s_waitcnt lgkmcnt(0)
	v_mfma_f32_32x32x16_bf16 v[66:81], v[174:177], v[110:113], v[66:81]
	v_fma_f32 v147, v147, -v119, -v139
	s_nop 10
	v_fmamk_f32 v66, v66, 0x3e0293ee, v147
	v_fmac_f32_e32 v66, 0, v119
	v_fmamk_f32 v67, v67, 0x3e0293ee, v147
	v_exp_f32_e32 v66, v66
	v_fmac_f32_e32 v67, 0x41800000, v119
	v_fmamk_f32 v68, v68, 0x3e0293ee, v147
	v_exp_f32_e32 v67, v67
	v_fmac_f32_e32 v68, 0x42000000, v119
	v_fmamk_f32 v69, v69, 0x3e0293ee, v147
	v_exp_f32_e32 v68, v68
	v_fmac_f32_e32 v69, 0x42400000, v119
	v_fmamk_f32 v70, v70, 0x3e0293ee, v147
	v_exp_f32_e32 v69, v69
	v_fmac_f32_e32 v70, 0x43000000, v119
	v_fmamk_f32 v71, v71, 0x3e0293ee, v147
	v_mul_f32_e32 v66, v123, v66
	v_exp_f32_e32 v70, v70
	v_fmac_f32_e32 v71, 0x43100000, v119
	v_fmamk_f32 v72, v72, 0x3e0293ee, v147
	v_cndmask_b32_e64 v66, 0, v66, s[40:41]
	v_mul_f32_e32 v67, v123, v67
	v_cmp_lt_i32_e64 s[40:41], 46, v146
	v_exp_f32_e32 v71, v71
	v_fmac_f32_e32 v72, 0x43200000, v119
	v_fmamk_f32 v73, v73, 0x3e0293ee, v147
	v_cndmask_b32_e64 v67, 0, v67, s[40:41]
	v_mul_f32_e32 v68, v123, v68
	v_cmp_lt_i32_e64 s[40:41], 62, v146
	v_exp_f32_e32 v72, v72
	v_fmac_f32_e32 v73, 0x43300000, v119
	v_fmamk_f32 v74, v74, 0x3e0293ee, v147
	v_cndmask_b32_e64 v68, 0, v68, s[40:41]
	v_mul_f32_e32 v69, v123, v69
	v_cmp_lt_i32_e64 s[40:41], s25, v146
	v_exp_f32_e32 v73, v73
	v_fmac_f32_e32 v74, 0x43800000, v119
	v_fmamk_f32 v75, v75, 0x3e0293ee, v147
	v_cndmask_b32_e64 v69, 0, v69, s[40:41]
	v_mul_f32_e32 v70, v123, v70
	v_cmp_lt_i32_e64 s[40:41], s28, v146
	v_exp_f32_e32 v74, v74
	v_fmac_f32_e32 v75, 0x43880000, v119
	v_fmamk_f32 v76, v76, 0x3e0293ee, v147
	v_cndmask_b32_e64 v70, 0, v70, s[40:41]
	v_mul_f32_e32 v71, v123, v71
	v_cmp_lt_i32_e64 s[40:41], s29, v146
	v_exp_f32_e32 v75, v75
	v_fmac_f32_e32 v76, 0x43900000, v119
	v_fmamk_f32 v77, v77, 0x3e0293ee, v147
	v_cndmask_b32_e64 v71, 0, v71, s[40:41]
	v_mul_f32_e32 v72, v123, v72
	v_cmp_lt_i32_e64 s[40:41], s30, v146
	v_exp_f32_e32 v76, v76
	v_fmac_f32_e32 v77, 0x43980000, v119
	v_fmamk_f32 v78, v78, 0x3e0293ee, v147
	v_cndmask_b32_e64 v72, 0, v72, s[40:41]
	v_mul_f32_e32 v73, v123, v73
	v_cmp_lt_i32_e64 s[40:41], s31, v146
	v_exp_f32_e32 v77, v77
	v_fmac_f32_e32 v78, 0x43c00000, v119
	v_fmamk_f32 v79, v79, 0x3e0293ee, v147
	v_cndmask_b32_e64 v73, 0, v73, s[40:41]
	v_mul_f32_e32 v74, v123, v74
	v_cmp_lt_i32_e64 s[40:41], s34, v146
	v_exp_f32_e32 v78, v78
	v_fmac_f32_e32 v79, 0x43c80000, v119
	v_fmamk_f32 v80, v80, 0x3e0293ee, v147
	v_cndmask_b32_e64 v74, 0, v74, s[40:41]
	v_mul_f32_e32 v75, v123, v75
	v_cmp_lt_i32_e64 s[40:41], s94, v146
	v_exp_f32_e32 v79, v79
	v_fmac_f32_e32 v80, 0x43d00000, v119
	v_cndmask_b32_e64 v75, 0, v75, s[40:41]
	v_mul_f32_e32 v76, v123, v76
	v_cmp_lt_i32_e64 s[40:41], s95, v146
	v_exp_f32_e32 v80, v80
	v_mul_f32_e32 v77, v123, v77
	v_cndmask_b32_e64 v76, 0, v76, s[40:41]
	v_cmp_lt_i32_e64 s[40:41], s73, v146
	v_mul_f32_e32 v78, v123, v78
	v_mul_f32_e32 v79, v123, v79
	v_cndmask_b32_e64 v77, 0, v77, s[40:41]
	v_cmp_lt_i32_e64 s[40:41], s3, v146
	v_mul_f32_e32 v80, v123, v80
	v_fmac_f32_e32 v147, 0x3e0293ee, v81
	v_cndmask_b32_e64 v78, 0, v78, s[40:41]
	v_cmp_lt_i32_e64 s[40:41], s89, v146
	v_fmac_f32_e32 v147, 0x43d80000, v119
	v_exp_f32_e32 v81, v147
	v_cndmask_b32_e64 v79, 0, v79, s[40:41]
	v_cmp_lt_i32_e64 s[40:41], s1, v146
	v_add_f32_e32 v147, v66, v67
	v_add_f32_e32 v147, v68, v147
	v_cndmask_b32_e64 v80, 0, v80, s[40:41]
	v_cmp_lt_i32_e64 s[40:41], s80, v146
	v_mul_f32_e32 v146, 0.5, v69
	ds_bpermute_b32 v146, v172, v146
	v_fmac_f32_e32 v147, 0.5, v69
	v_add_f32_e32 v148, v70, v71
	v_add_f32_e32 v148, v72, v148
	v_fmac_f32_e32 v148, 0.5, v73
	s_waitcnt lgkmcnt(0)
	v_cndmask_b32_e32 v140, v146, v140, vcc
	v_add_f32_e32 v147, v140, v147
	v_mul_f32_e32 v140, 0.5, v73
	ds_bpermute_b32 v140, v172, v140
	v_mul_f32_e32 v81, v123, v81
	v_cndmask_b32_e64 v81, 0, v81, s[40:41]
	s_waitcnt lgkmcnt(0)
	v_cndmask_b32_e32 v146, v140, v146, vcc
	v_add_f32_e32 v148, v146, v148
	v_mul_f32_e32 v146, 0.5, v77
	ds_bpermute_b32 v150, v172, v146
	v_add_f32_e32 v146, v74, v75
	v_add_f32_e32 v146, v76, v146
	v_fmac_f32_e32 v146, 0.5, v77
	s_waitcnt lgkmcnt(0)
	v_cndmask_b32_e32 v140, v150, v140, vcc
	v_add_f32_e32 v146, v140, v146
	v_mul_f32_e32 v140, 0.5, v81
	ds_bpermute_b32 v151, v172, v140
	v_add_f32_e32 v140, v78, v79
	v_add_f32_e32 v140, v80, v140
	v_fmac_f32_e32 v140, 0.5, v81
	s_waitcnt lgkmcnt(0)
	v_cndmask_b32_e32 v150, v151, v150, vcc
	v_add_f32_e32 v140, v150, v140
	v_cvt_pk_bf16_f32 v66, v66, v67
	v_cvt_pk_bf16_f32 v67, v68, v69
	v_cvt_pk_bf16_f32 v68, v70, v71
	v_cvt_pk_bf16_f32 v69, v72, v73
	ds_read2_b64 v[70:73], v144 offset0:8 offset1:10
	s_waitcnt lgkmcnt(0)
	v_mfma_f32_32x32x16_bf16 v[50:65], v[70:73], v[66:69], v[50:65]
	ds_read2_b64 v[70:73], v141 offset0:8 offset1:10
	s_waitcnt lgkmcnt(0)
	v_mfma_f32_32x32x16_bf16 v[34:49], v[70:73], v[66:69], v[34:49]
	ds_read2_b64 v[70:73], v142 offset0:136 offset1:138
	s_waitcnt lgkmcnt(0)
	v_mfma_f32_32x32x16_bf16 v[18:33], v[70:73], v[66:69], v[18:33]
	ds_read2_b64 v[70:73], v143 offset0:8 offset1:10
	s_waitcnt lgkmcnt(0)
	v_mfma_f32_32x32x16_bf16 v[2:17], v[70:73], v[66:69], v[2:17]
	ds_read2_b64 v[70:73], v144 offset0:12 offset1:14
	v_cvt_pk_bf16_f32 v66, v74, v75
	v_cvt_pk_bf16_f32 v67, v76, v77
	v_cvt_pk_bf16_f32 v68, v78, v79
	v_cvt_pk_bf16_f32 v69, v80, v81
	s_waitcnt lgkmcnt(0)
	s_nop 0
	v_mfma_f32_32x32x16_bf16 v[50:65], v[70:73], v[66:69], v[50:65]
	ds_read2_b64 v[70:73], v141 offset0:12 offset1:14
	s_waitcnt lgkmcnt(0)
	v_mfma_f32_32x32x16_bf16 v[34:49], v[70:73], v[66:69], v[34:49]
	ds_read2_b64 v[70:73], v142 offset0:140 offset1:142
	s_waitcnt lgkmcnt(0)
	v_mfma_f32_32x32x16_bf16 v[18:33], v[70:73], v[66:69], v[18:33]
	ds_read2_b64 v[70:73], v143 offset0:12 offset1:14
	s_waitcnt lgkmcnt(0)
	v_mfma_f32_32x32x16_bf16 v[2:17], v[70:73], v[66:69], v[2:17]
	ds_read_b128 v[66:69], v149 offset:17408
	ds_read_b128 v[174:177], v149 offset:17440
	s_waitcnt lgkmcnt(1)
	v_mfma_f32_32x32x16_bf16 v[66:81], v[66:69], v[82:85], 0
	s_waitcnt lgkmcnt(0)
	v_mfma_f32_32x32x16_bf16 v[66:81], v[174:177], v[86:89], v[66:81]
	ds_read_b128 v[174:177], v149 offset:17472
	ds_read_b128 v[178:181], v149 offset:17504
	s_waitcnt lgkmcnt(1)
	v_mfma_f32_32x32x16_bf16 v[66:81], v[174:177], v[90:93], v[66:81]
	s_waitcnt lgkmcnt(0)
	v_mfma_f32_32x32x16_bf16 v[66:81], v[178:181], v[94:97], v[66:81]
	ds_read_b128 v[174:177], v149 offset:17536
	ds_read_b128 v[178:181], v149 offset:17568
	s_waitcnt lgkmcnt(1)
	v_mfma_f32_32x32x16_bf16 v[66:81], v[174:177], v[98:101], v[66:81]
	s_waitcnt lgkmcnt(0)
	v_mfma_f32_32x32x16_bf16 v[66:81], v[178:181], v[102:105], v[66:81]
	ds_read_b128 v[174:177], v149 offset:17600
	ds_read_b128 v[178:181], v149 offset:17632
	v_or_b32_e32 v149, 0x400, v0
	v_sub_u32_e32 v149, v117, v149
	v_cvt_f32_i32_e32 v150, v149
	v_cmp_lt_i32_e64 s[40:41], 30, v149
	v_add_f32_e32 v150, 0xc1780000, v150
	s_waitcnt lgkmcnt(1)
	v_mfma_f32_32x32x16_bf16 v[66:81], v[174:177], v[106:109], v[66:81]
	v_fma_f32 v150, v150, -v119, -v139
	s_waitcnt lgkmcnt(0)
	v_mfma_f32_32x32x16_bf16 v[66:81], v[178:181], v[110:113], v[66:81]
	s_nop 11
	v_fmamk_f32 v66, v66, 0x3e0293ee, v150
	v_fmamk_f32 v67, v67, 0x3e0293ee, v150
	v_fmac_f32_e32 v66, 0, v119
	v_fmamk_f32 v68, v68, 0x3e0293ee, v150
	v_fmac_f32_e32 v67, 0x41800000, v119
	v_exp_f32_e32 v66, v66
	v_fmamk_f32 v69, v69, 0x3e0293ee, v150
	v_fmac_f32_e32 v68, 0x42000000, v119
	v_exp_f32_e32 v67, v67
	v_fmamk_f32 v70, v70, 0x3e0293ee, v150
	v_fmac_f32_e32 v69, 0x42400000, v119
	v_exp_f32_e32 v68, v68
	v_fmamk_f32 v71, v71, 0x3e0293ee, v150
	v_fmac_f32_e32 v70, 0x43000000, v119
	v_exp_f32_e32 v69, v69
	v_fmamk_f32 v72, v72, 0x3e0293ee, v150
	v_fmac_f32_e32 v71, 0x43100000, v119
	v_exp_f32_e32 v70, v70
	v_mul_f32_e32 v66, v123, v66
	v_fmamk_f32 v73, v73, 0x3e0293ee, v150
	v_fmac_f32_e32 v72, 0x43200000, v119
	v_exp_f32_e32 v71, v71
	v_mul_f32_e32 v67, v123, v67
	v_cndmask_b32_e64 v66, 0, v66, s[40:41]
	v_cmp_lt_i32_e64 s[40:41], 46, v149
	v_fmamk_f32 v74, v74, 0x3e0293ee, v150
	v_fmac_f32_e32 v73, 0x43300000, v119
	v_exp_f32_e32 v72, v72
	v_mul_f32_e32 v68, v123, v68
	v_cndmask_b32_e64 v67, 0, v67, s[40:41]
	v_cmp_lt_i32_e64 s[40:41], 62, v149
	v_fmamk_f32 v75, v75, 0x3e0293ee, v150
	v_fmac_f32_e32 v74, 0x43800000, v119
	v_exp_f32_e32 v73, v73
	v_mul_f32_e32 v69, v123, v69
	v_cndmask_b32_e64 v68, 0, v68, s[40:41]
	v_cmp_lt_i32_e64 s[40:41], s25, v149
	v_fmac_f32_e32 v75, 0x43880000, v119
	v_exp_f32_e32 v74, v74
	v_mul_f32_e32 v70, v123, v70
	v_cndmask_b32_e64 v69, 0, v69, s[40:41]
	v_cmp_lt_i32_e64 s[40:41], s28, v149
	v_fmamk_f32 v76, v76, 0x3e0293ee, v150
	v_exp_f32_e32 v75, v75
	v_mul_f32_e32 v71, v123, v71
	v_cndmask_b32_e64 v70, 0, v70, s[40:41]
	v_cmp_lt_i32_e64 s[40:41], s29, v149
	v_fmac_f32_e32 v76, 0x43900000, v119
	v_fmamk_f32 v77, v77, 0x3e0293ee, v150
	v_mul_f32_e32 v72, v123, v72
	v_cndmask_b32_e64 v71, 0, v71, s[40:41]
	v_cmp_lt_i32_e64 s[40:41], s30, v149
	v_exp_f32_e32 v76, v76
	v_fmac_f32_e32 v77, 0x43980000, v119
	v_fmamk_f32 v78, v78, 0x3e0293ee, v150
	v_mul_f32_e32 v73, v123, v73
	v_cndmask_b32_e64 v72, 0, v72, s[40:41]
	v_cmp_lt_i32_e64 s[40:41], s31, v149
	v_exp_f32_e32 v77, v77
	v_fmac_f32_e32 v78, 0x43c00000, v119
	v_fmamk_f32 v79, v79, 0x3e0293ee, v150
	v_mul_f32_e32 v74, v123, v74
	v_cndmask_b32_e64 v73, 0, v73, s[40:41]
	v_cmp_lt_i32_e64 s[40:41], s34, v149
	v_exp_f32_e32 v78, v78
	v_fmac_f32_e32 v79, 0x43c80000, v119
	v_fmamk_f32 v80, v80, 0x3e0293ee, v150
	v_mul_f32_e32 v75, v123, v75
	v_cndmask_b32_e64 v74, 0, v74, s[40:41]
	v_cmp_lt_i32_e64 s[40:41], s94, v149
	v_exp_f32_e32 v79, v79
	v_fmac_f32_e32 v80, 0x43d00000, v119
	v_fmac_f32_e32 v150, 0x3e0293ee, v81
	v_cndmask_b32_e64 v75, 0, v75, s[40:41]
	v_mul_f32_e32 v76, v123, v76
	v_cmp_lt_i32_e64 s[40:41], s95, v149
	v_exp_f32_e32 v80, v80
	v_fmac_f32_e32 v150, 0x43d80000, v119
	v_cndmask_b32_e64 v76, 0, v76, s[40:41]
	v_mul_f32_e32 v77, v123, v77
	v_cmp_lt_i32_e64 s[40:41], s73, v149
	v_exp_f32_e32 v81, v150
	v_mul_f32_e32 v150, 0.5, v69
	v_cndmask_b32_e64 v77, 0, v77, s[40:41]
	v_mul_f32_e32 v78, v123, v78
	v_cmp_lt_i32_e64 s[40:41], s3, v149
	ds_bpermute_b32 v150, v172, v150
	v_mul_f32_e32 v79, v123, v79
	v_cndmask_b32_e64 v78, 0, v78, s[40:41]
	v_cmp_lt_i32_e64 s[40:41], s89, v149
	v_mul_f32_e32 v80, v123, v80
	s_waitcnt lgkmcnt(0)
	v_cndmask_b32_e32 v151, v150, v151, vcc
	v_cndmask_b32_e64 v79, 0, v79, s[40:41]
	v_cmp_lt_i32_e64 s[40:41], s1, v149
	v_mul_f32_e32 v152, 0.5, v73
	ds_bpermute_b32 v154, v172, v152
	v_cndmask_b32_e64 v80, 0, v80, s[40:41]
	v_cmp_lt_i32_e64 s[40:41], s80, v149
	v_add_f32_e32 v149, v66, v67
	v_add_f32_e32 v149, v68, v149
	v_fmac_f32_e32 v149, 0.5, v69
	v_add_f32_e32 v152, v151, v149
	v_mul_f32_e32 v151, 0.5, v77
	ds_bpermute_b32 v155, v172, v151
	v_add_f32_e32 v149, v70, v71
	v_mul_f32_e32 v81, v123, v81
	v_add_f32_e32 v149, v72, v149
	v_cndmask_b32_e64 v81, 0, v81, s[40:41]
	v_fmac_f32_e32 v149, 0.5, v73
	s_waitcnt lgkmcnt(1)
	v_cndmask_b32_e32 v150, v154, v150, vcc
	v_add_f32_e32 v151, v150, v149
	s_waitcnt lgkmcnt(0)
	v_cndmask_b32_e32 v150, v155, v154, vcc
	v_mul_f32_e32 v154, 0.5, v81
	v_add_f32_e32 v149, v74, v75
	ds_bpermute_b32 v154, v172, v154
	v_add_f32_e32 v149, v76, v149
	v_fmac_f32_e32 v149, 0.5, v77
	v_add_f32_e32 v150, v150, v149
	v_add_f32_e32 v149, v78, v79
	v_add_f32_e32 v149, v80, v149
	v_fmac_f32_e32 v149, 0.5, v81
	s_waitcnt lgkmcnt(0)
	v_cndmask_b32_e32 v155, v154, v155, vcc
	v_add_f32_e32 v149, v155, v149
	v_cvt_pk_bf16_f32 v66, v66, v67
	v_cvt_pk_bf16_f32 v67, v68, v69
	v_cvt_pk_bf16_f32 v68, v70, v71
	v_cvt_pk_bf16_f32 v69, v72, v73
	ds_read2_b64 v[70:73], v144 offset0:16 offset1:18
	s_waitcnt lgkmcnt(0)
	v_mfma_f32_32x32x16_bf16 v[50:65], v[70:73], v[66:69], v[50:65]
	ds_read2_b64 v[70:73], v141 offset0:16 offset1:18
	s_waitcnt lgkmcnt(0)
	v_mfma_f32_32x32x16_bf16 v[34:49], v[70:73], v[66:69], v[34:49]
	ds_read2_b64 v[70:73], v142 offset0:144 offset1:146
	s_waitcnt lgkmcnt(0)
	v_mfma_f32_32x32x16_bf16 v[18:33], v[70:73], v[66:69], v[18:33]
	ds_read2_b64 v[70:73], v143 offset0:16 offset1:18
	s_waitcnt lgkmcnt(0)
	v_mfma_f32_32x32x16_bf16 v[2:17], v[70:73], v[66:69], v[2:17]
	ds_read2_b64 v[70:73], v144 offset0:20 offset1:22
	v_cvt_pk_bf16_f32 v66, v74, v75
	v_cvt_pk_bf16_f32 v67, v76, v77
	v_cvt_pk_bf16_f32 v68, v78, v79
	v_cvt_pk_bf16_f32 v69, v80, v81
	s_waitcnt lgkmcnt(0)
	s_nop 0
	v_mfma_f32_32x32x16_bf16 v[50:65], v[70:73], v[66:69], v[50:65]
	ds_read2_b64 v[70:73], v141 offset0:20 offset1:22
	s_waitcnt lgkmcnt(0)
	v_mfma_f32_32x32x16_bf16 v[34:49], v[70:73], v[66:69], v[34:49]
	ds_read2_b64 v[70:73], v142 offset0:148 offset1:150
	s_waitcnt lgkmcnt(0)
	v_mfma_f32_32x32x16_bf16 v[18:33], v[70:73], v[66:69], v[18:33]
	ds_read2_b64 v[70:73], v143 offset0:20 offset1:22
	s_waitcnt lgkmcnt(0)
	v_mfma_f32_32x32x16_bf16 v[2:17], v[70:73], v[66:69], v[2:17]
	v_add_u32_e32 v145, v145, v153
	ds_read_b128 v[66:69], v145
	ds_read_b128 v[174:177], v145 offset:32
	v_or_b32_e32 v0, 0x600, v0
	v_sub_u32_e32 v0, v117, v0
	v_cmp_lt_i32_e64 s[40:41], 30, v0
	s_waitcnt lgkmcnt(1)
	v_mfma_f32_32x32x16_bf16 v[66:81], v[66:69], v[82:85], 0
	s_waitcnt lgkmcnt(0)
	v_mfma_f32_32x32x16_bf16 v[66:81], v[174:177], v[86:89], v[66:81]
	ds_read_b128 v[174:177], v145 offset:64
	ds_read_b128 v[178:181], v145 offset:96
	s_waitcnt lgkmcnt(1)
	v_mfma_f32_32x32x16_bf16 v[66:81], v[174:177], v[90:93], v[66:81]
	s_waitcnt lgkmcnt(0)
	v_mfma_f32_32x32x16_bf16 v[66:81], v[178:181], v[94:97], v[66:81]
	ds_read_b128 v[174:177], v145 offset:128
	ds_read_b128 v[178:181], v145 offset:160
	s_waitcnt lgkmcnt(1)
	v_mfma_f32_32x32x16_bf16 v[66:81], v[174:177], v[98:101], v[66:81]
	ds_read_b128 v[174:177], v145 offset:192
	s_waitcnt lgkmcnt(1)
	v_mfma_f32_32x32x16_bf16 v[66:81], v[178:181], v[102:105], v[66:81]
	ds_read_b128 v[178:181], v145 offset:224
	v_cvt_f32_i32_e32 v145, v0
	v_add_f32_e32 v145, 0xc1780000, v145
	v_fma_f32 v139, v145, -v119, -v139
	s_waitcnt lgkmcnt(1)
	v_mfma_f32_32x32x16_bf16 v[66:81], v[174:177], v[106:109], v[66:81]
	s_waitcnt lgkmcnt(0)
	v_mfma_f32_32x32x16_bf16 v[66:81], v[178:181], v[110:113], v[66:81]
	s_nop 11
	v_fmamk_f32 v66, v66, 0x3e0293ee, v139
	v_fmamk_f32 v67, v67, 0x3e0293ee, v139
	v_fmac_f32_e32 v66, 0, v119
	v_fmamk_f32 v68, v68, 0x3e0293ee, v139
	v_fmac_f32_e32 v67, 0x41800000, v119
	v_exp_f32_e32 v66, v66
	v_fmamk_f32 v69, v69, 0x3e0293ee, v139
	v_fmac_f32_e32 v68, 0x42000000, v119
	v_exp_f32_e32 v67, v67
	v_fmamk_f32 v70, v70, 0x3e0293ee, v139
	v_fmac_f32_e32 v69, 0x42400000, v119
	v_exp_f32_e32 v68, v68
	v_fmamk_f32 v71, v71, 0x3e0293ee, v139
	v_fmac_f32_e32 v70, 0x43000000, v119
	v_exp_f32_e32 v69, v69
	v_fmamk_f32 v72, v72, 0x3e0293ee, v139
	v_fmac_f32_e32 v71, 0x43100000, v119
	v_exp_f32_e32 v70, v70
	v_mul_f32_e32 v66, v123, v66
	v_fmamk_f32 v73, v73, 0x3e0293ee, v139
	v_fmac_f32_e32 v72, 0x43200000, v119
	v_exp_f32_e32 v71, v71
	v_mul_f32_e32 v67, v123, v67
	v_cndmask_b32_e64 v66, 0, v66, s[40:41]
	v_cmp_lt_i32_e64 s[40:41], 46, v0
	v_fmamk_f32 v74, v74, 0x3e0293ee, v139
	v_fmac_f32_e32 v73, 0x43300000, v119
	v_exp_f32_e32 v72, v72
	v_mul_f32_e32 v68, v123, v68
	v_cndmask_b32_e64 v67, 0, v67, s[40:41]
	v_cmp_lt_i32_e64 s[40:41], 62, v0
	v_fmamk_f32 v75, v75, 0x3e0293ee, v139
	v_fmac_f32_e32 v74, 0x43800000, v119
	v_exp_f32_e32 v73, v73
	v_mul_f32_e32 v69, v123, v69
	v_cndmask_b32_e64 v145, 0, v68, s[40:41]
	v_cmp_lt_i32_e64 s[40:41], s25, v0
	v_fmac_f32_e32 v75, 0x43880000, v119
	v_exp_f32_e32 v74, v74
	v_mul_f32_e32 v70, v123, v70
	v_cndmask_b32_e64 v153, 0, v69, s[40:41]
	v_cmp_lt_i32_e64 s[40:41], s28, v0
	v_fmamk_f32 v68, v76, 0x3e0293ee, v139
	v_exp_f32_e32 v75, v75
	v_mul_f32_e32 v71, v123, v71
	v_cndmask_b32_e64 v155, 0, v70, s[40:41]
	v_cmp_lt_i32_e64 s[40:41], s29, v0
	v_fmac_f32_e32 v68, 0x43900000, v119
	v_fmamk_f32 v69, v77, 0x3e0293ee, v139
	v_mul_f32_e32 v72, v123, v72
	v_cndmask_b32_e64 v174, 0, v71, s[40:41]
	v_cmp_lt_i32_e64 s[40:41], s30, v0
	v_exp_f32_e32 v68, v68
	v_fmac_f32_e32 v69, 0x43980000, v119
	v_mul_f32_e32 v73, v123, v73
	v_cndmask_b32_e64 v175, 0, v72, s[40:41]
	v_cmp_lt_i32_e64 s[40:41], s31, v0
	v_exp_f32_e32 v69, v69
	v_mul_f32_e32 v74, v123, v74
	v_cndmask_b32_e64 v176, 0, v73, s[40:41]
	v_cmp_lt_i32_e64 s[40:41], s34, v0
	v_mul_f32_e32 v75, v123, v75
	v_mul_f32_e32 v68, v123, v68
	v_cndmask_b32_e64 v177, 0, v74, s[40:41]
	v_cmp_lt_i32_e64 s[40:41], s94, v0
	v_mul_f32_e32 v71, 0.5, v176
	ds_bpermute_b32 v72, v172, v71
	v_cndmask_b32_e64 v178, 0, v75, s[40:41]
	v_cmp_lt_i32_e64 s[40:41], s95, v0
	s_nop 1
	v_cndmask_b32_e64 v179, 0, v68, s[40:41]
	v_mul_f32_e32 v68, v123, v69
	v_cmp_lt_i32_e64 s[40:41], s73, v0
	v_fmamk_f32 v69, v79, 0x3e0293ee, v139
	v_fmac_f32_e32 v69, 0x43c80000, v119
	v_cndmask_b32_e64 v180, 0, v68, s[40:41]
	v_fmamk_f32 v68, v78, 0x3e0293ee, v139
	v_fmac_f32_e32 v68, 0x43c00000, v119
	v_exp_f32_e32 v68, v68
	v_exp_f32_e32 v69, v69
	v_cmp_lt_i32_e64 s[40:41], s3, v0
	v_mul_f32_e32 v68, v123, v68
	s_nop 0
	v_cndmask_b32_e64 v181, 0, v68, s[40:41]
	v_mul_f32_e32 v68, v123, v69
	v_cmp_lt_i32_e64 s[40:41], s89, v0
	s_nop 1
	v_cndmask_b32_e64 v182, 0, v68, s[40:41]
	v_fmamk_f32 v68, v80, 0x3e0293ee, v139
	v_fmac_f32_e32 v68, 0x43d00000, v119
	v_fmac_f32_e32 v139, 0x3e0293ee, v81
	v_exp_f32_e32 v68, v68
	v_fmac_f32_e32 v139, 0x43d80000, v119
	v_exp_f32_e32 v69, v139
	v_cmp_lt_i32_e64 s[40:41], s1, v0
	v_mul_f32_e32 v68, v123, v68
	s_nop 0
	v_cndmask_b32_e64 v80, 0, v68, s[40:41]
	v_mul_f32_e32 v68, v123, v69
	v_mul_f32_e32 v69, 0.5, v153
	ds_bpermute_b32 v69, v172, v69
	v_cmp_lt_i32_e64 s[40:41], s80, v0
	s_waitcnt lgkmcnt(0)
	v_cndmask_b32_e32 v70, v69, v154, vcc
	v_cndmask_b32_e64 v0, 0, v68, s[40:41]
	v_add_f32_e32 v68, v66, v67
	v_add_f32_e32 v68, v145, v68
	v_fmac_f32_e32 v68, 0.5, v153
	v_add_f32_e32 v71, v70, v68
	v_mul_f32_e32 v70, 0.5, v180
	ds_bpermute_b32 v73, v172, v70
	v_add_f32_e32 v68, v155, v174
	v_add_f32_e32 v68, v175, v68
	v_fmac_f32_e32 v68, 0.5, v176
	v_cndmask_b32_e32 v69, v72, v69, vcc
	v_add_f32_e32 v70, v69, v68
	s_waitcnt lgkmcnt(0)
	v_cndmask_b32_e32 v69, v73, v72, vcc
	v_mul_f32_e32 v72, 0.5, v0
	v_add_f32_e32 v68, v177, v178
	ds_bpermute_b32 v72, v172, v72
	v_add_f32_e32 v68, v179, v68
	v_fmac_f32_e32 v68, 0.5, v180
	v_add_f32_e32 v69, v69, v68
	v_add_f32_e32 v68, v181, v182
	v_add_f32_e32 v68, v80, v68
	v_fmac_f32_e32 v68, 0.5, v0
	s_waitcnt lgkmcnt(0)
	v_cndmask_b32_e32 v72, v72, v73, vcc
	v_add_f32_e32 v68, v72, v68
	ds_read2_b64 v[76:79], v144 offset0:24 offset1:26
	v_cvt_pk_bf16_f32 v72, v66, v67
	v_cvt_pk_bf16_f32 v73, v145, v153
	v_cvt_pk_bf16_f32 v74, v155, v174
	v_cvt_pk_bf16_f32 v75, v175, v176
	s_waitcnt lgkmcnt(0)
	s_nop 0
	v_mfma_f32_32x32x16_bf16 v[50:65], v[76:79], v[72:75], v[50:65]
	ds_read2_b64 v[76:79], v141 offset0:24 offset1:26
	s_waitcnt lgkmcnt(0)
	v_mfma_f32_32x32x16_bf16 v[34:49], v[76:79], v[72:75], v[34:49]
	ds_read2_b64 v[76:79], v142 offset0:152 offset1:154
	s_waitcnt lgkmcnt(0)
	v_mfma_f32_32x32x16_bf16 v[18:33], v[76:79], v[72:75], v[18:33]
	ds_read2_b64 v[76:79], v143 offset0:24 offset1:26
	s_waitcnt lgkmcnt(0)
	v_mfma_f32_32x32x16_bf16 v[2:17], v[76:79], v[72:75], v[2:17]
	ds_read2_b64 v[76:79], v144 offset0:28 offset1:30
	v_cvt_pk_bf16_f32 v72, v177, v178
	v_cvt_pk_bf16_f32 v73, v179, v180
	v_cvt_pk_bf16_f32 v74, v181, v182
	v_cvt_pk_bf16_f32 v75, v80, v0
	s_waitcnt lgkmcnt(0)
	s_nop 0
	v_mfma_f32_32x32x16_bf16 v[50:65], v[76:79], v[72:75], v[50:65]
	ds_read2_b64 v[76:79], v141 offset0:28 offset1:30
	s_waitcnt lgkmcnt(0)
	v_mfma_f32_32x32x16_bf16 v[34:49], v[76:79], v[72:75], v[34:49]
	ds_read2_b64 v[76:79], v142 offset0:156 offset1:158
	s_waitcnt lgkmcnt(0)
	v_mfma_f32_32x32x16_bf16 v[18:33], v[76:79], v[72:75], v[18:33]
	ds_read2_b64 v[76:79], v143 offset0:28 offset1:30
	s_waitcnt lgkmcnt(0)
	v_mfma_f32_32x32x16_bf16 v[2:17], v[76:79], v[72:75], v[2:17]
	v_mul_u32_u24_e32 v74, 3, v129
	v_lshlrev_b32_e32 v0, 1, v74
	v_lshl_add_u64 v[66:67], v[124:125], 0, v[0:1]
	s_movk_i32 s25, 0x1000
	v_add_co_u32_e32 v72, vcc, s25, v66
	s_load_dwordx2 s[40:41], s[12:13], 0x20
	s_nop 0
	v_addc_co_u32_e32 v73, vcc, 0, v67, vcc
	s_nop 0
	s_load_dwordx2 s[28:29], s[12:13], 0x100
	v_lshlrev_b32_e32 v76, 2, v116
	v_mov_b32_e32 v77, v1
	v_mov_b32_e32 v123, v1
	s_waitcnt vmcnt(0)
	v_lshlrev_b32_e32 v72, 16, v208
	v_lshlrev_b32_e32 v0, 2, v74
	s_waitcnt lgkmcnt(0)
	v_mov_b32_e32 v73, v211
	v_lshlrev_b64 v[74:75], 13, v[114:115]
	v_lshl_add_u64 v[74:75], s[28:29], 0, v[74:75]
	v_lshl_add_u64 v[74:75], v[74:75], 0, v[76:77]
	v_lshl_add_u64 v[122:123], v[74:75], 0, v[122:123]
	v_lshlrev_b32_e32 v115, 2, v135
	s_waitcnt vmcnt(0)
	v_add_f32_e32 v72, v73, v72
	v_mul_f32_e32 v72, 0xbfb8aa3b, v72
	v_exp_f32_e32 v72, v72
	s_nop 0
	v_add_f32_e32 v72, 1.0, v72
	v_rcp_f32_e32 v72, v72
	s_nop 0
	v_pk_mul_f32 v[2:3], v[2:3], v[72:73] op_sel_hi:[1,0]
	v_pk_mul_f32 v[4:5], v[4:5], v[72:73] op_sel_hi:[1,0]
	global_store_dwordx4 v[122:123], v[2:5], off offset:384
	v_pk_mul_f32 v[18:19], v[18:19], v[72:73] op_sel_hi:[1,0]
	v_pk_mul_f32 v[20:21], v[20:21], v[72:73] op_sel_hi:[1,0]
	v_pk_mul_f32 v[2:3], v[6:7], v[72:73] op_sel_hi:[1,0]
	v_pk_mul_f32 v[4:5], v[8:9], v[72:73] op_sel_hi:[1,0]
	global_store_dwordx4 v[122:123], v[2:5], off offset:416
	global_store_dwordx4 v[122:123], v[18:21], off offset:256
	v_pk_mul_f32 v[50:51], v[50:51], v[72:73] op_sel_hi:[1,0]
	v_pk_mul_f32 v[2:3], v[10:11], v[72:73] op_sel_hi:[1,0]
	v_pk_mul_f32 v[4:5], v[12:13], v[72:73] op_sel_hi:[1,0]
	global_store_dwordx4 v[122:123], v[2:5], off offset:448
	v_pk_mul_f32 v[18:19], v[22:23], v[72:73] op_sel_hi:[1,0]
	v_pk_mul_f32 v[20:21], v[24:25], v[72:73] op_sel_hi:[1,0]
	v_pk_mul_f32 v[2:3], v[14:15], v[72:73] op_sel_hi:[1,0]
	v_pk_mul_f32 v[4:5], v[16:17], v[72:73] op_sel_hi:[1,0]
	global_store_dwordx4 v[122:123], v[2:5], off offset:480
	global_store_dwordx4 v[122:123], v[18:21], off offset:288
	v_pk_mul_f32 v[52:53], v[52:53], v[72:73] op_sel_hi:[1,0]
	v_xor_b32_e32 v2, 1, v160
	v_cmp_lt_i32_e32 vcc, v2, v128
	v_pk_mul_f32 v[18:19], v[26:27], v[72:73] op_sel_hi:[1,0]
	v_pk_mul_f32 v[20:21], v[28:29], v[72:73] op_sel_hi:[1,0]
	v_cndmask_b32_e32 v2, v160, v2, vcc
	v_lshlrev_b32_e32 v6, 2, v2
	v_xor_b32_e32 v2, 2, v160
	v_cmp_lt_i32_e32 vcc, v2, v128
	global_store_dwordx4 v[122:123], v[18:21], off offset:320
	ds_bpermute_b32 v4, v6, v137
	v_cndmask_b32_e32 v2, v160, v2, vcc
	v_pk_mul_f32 v[18:19], v[30:31], v[72:73] op_sel_hi:[1,0]
	v_pk_mul_f32 v[20:21], v[32:33], v[72:73] op_sel_hi:[1,0]
	global_store_dwordx4 v[122:123], v[18:21], off offset:352
	v_lshlrev_b32_e32 v8, 2, v2
	ds_bpermute_b32 v2, v6, v138
	ds_bpermute_b32 v7, v6, v136
	ds_bpermute_b32 v10, v6, v133
	ds_bpermute_b32 v12, v6, v147
	ds_bpermute_b32 v14, v6, v148
	ds_bpermute_b32 v16, v6, v146
	ds_bpermute_b32 v18, v6, v140
	ds_bpermute_b32 v20, v6, v152
	ds_bpermute_b32 v22, v6, v151
	ds_bpermute_b32 v24, v6, v150
	ds_bpermute_b32 v26, v6, v149
	ds_bpermute_b32 v28, v6, v71
	ds_bpermute_b32 v30, v6, v70
	ds_bpermute_b32 v32, v6, v69
	ds_bpermute_b32 v6, v6, v68
	s_waitcnt lgkmcnt(14)
	v_add_f32_e32 v2, v138, v2
	v_add_f32_e32 v4, v137, v4
	s_waitcnt lgkmcnt(13)
	v_add_f32_e32 v7, v136, v7
	s_waitcnt lgkmcnt(12)
	v_add_f32_e32 v10, v133, v10
	s_waitcnt lgkmcnt(11)
	v_add_f32_e32 v12, v147, v12
	s_waitcnt lgkmcnt(10)
	v_add_f32_e32 v14, v148, v14
	s_waitcnt lgkmcnt(9)
	v_add_f32_e32 v16, v146, v16
	s_waitcnt lgkmcnt(8)
	v_add_f32_e32 v18, v140, v18
	s_waitcnt lgkmcnt(7)
	v_add_f32_e32 v20, v152, v20
	s_waitcnt lgkmcnt(6)
	v_add_f32_e32 v22, v151, v22
	s_waitcnt lgkmcnt(5)
	v_add_f32_e32 v24, v150, v24
	s_waitcnt lgkmcnt(4)
	v_add_f32_e32 v26, v149, v26
	s_waitcnt lgkmcnt(3)
	v_add_f32_e32 v28, v71, v28
	s_waitcnt lgkmcnt(2)
	v_add_f32_e32 v30, v70, v30
	s_waitcnt lgkmcnt(1)
	v_add_f32_e32 v32, v69, v32
	s_waitcnt lgkmcnt(0)
	v_add_f32_e32 v6, v68, v6
	ds_bpermute_b32 v3, v8, v2
	ds_bpermute_b32 v5, v8, v4
	ds_bpermute_b32 v9, v8, v7
	ds_bpermute_b32 v11, v8, v10
	ds_bpermute_b32 v13, v8, v12
	ds_bpermute_b32 v15, v8, v14
	ds_bpermute_b32 v17, v8, v16
	ds_bpermute_b32 v19, v8, v18
	ds_bpermute_b32 v21, v8, v20
	ds_bpermute_b32 v23, v8, v22
	ds_bpermute_b32 v25, v8, v24
	ds_bpermute_b32 v27, v8, v26
	ds_bpermute_b32 v29, v8, v28
	ds_bpermute_b32 v31, v8, v30
	ds_bpermute_b32 v33, v8, v32
	ds_bpermute_b32 v8, v8, v6
	v_pk_mul_f32 v[34:35], v[34:35], v[72:73] op_sel_hi:[1,0]
	v_pk_mul_f32 v[36:37], v[36:37], v[72:73] op_sel_hi:[1,0]
	global_store_dwordx4 v[122:123], v[50:53], off
	global_store_dwordx4 v[122:123], v[34:37], off offset:128
	v_cmp_eq_u32_e32 vcc, 0, v127
	v_pk_mul_f32 v[50:51], v[54:55], v[72:73] op_sel_hi:[1,0]
	v_pk_mul_f32 v[52:53], v[56:57], v[72:73] op_sel_hi:[1,0]
	v_pk_mul_f32 v[34:35], v[38:39], v[72:73] op_sel_hi:[1,0]
	v_pk_mul_f32 v[36:37], v[40:41], v[72:73] op_sel_hi:[1,0]
	global_store_dwordx4 v[122:123], v[50:53], off offset:32
	global_store_dwordx4 v[122:123], v[34:37], off offset:160
	s_nop 0
	v_pk_mul_f32 v[50:51], v[58:59], v[72:73] op_sel_hi:[1,0]
	v_pk_mul_f32 v[52:53], v[60:61], v[72:73] op_sel_hi:[1,0]
	v_pk_mul_f32 v[34:35], v[42:43], v[72:73] op_sel_hi:[1,0]
	v_pk_mul_f32 v[36:37], v[44:45], v[72:73] op_sel_hi:[1,0]
	global_store_dwordx4 v[122:123], v[50:53], off offset:64
	global_store_dwordx4 v[122:123], v[34:37], off offset:192
	s_nop 0
	v_pk_mul_f32 v[50:51], v[62:63], v[72:73] op_sel_hi:[1,0]
	v_pk_mul_f32 v[52:53], v[64:65], v[72:73] op_sel_hi:[1,0]
	v_pk_mul_f32 v[34:35], v[46:47], v[72:73] op_sel_hi:[1,0]
	v_pk_mul_f32 v[36:37], v[48:49], v[72:73] op_sel_hi:[1,0]
	global_store_dwordx4 v[122:123], v[50:53], off offset:96
	global_store_dwordx4 v[122:123], v[34:37], off offset:224
	s_waitcnt lgkmcnt(0)
	s_barrier
	s_and_saveexec_b64 s[42:43], vcc
	s_cbranch_execz .LBB0_312
	v_add_f32_e32 v2, v2, v3
	v_or_b32_e32 v3, v126, v121
	v_lshlrev_b32_e32 v3, 7, v3
	v_add_f32_e32 v4, v4, v5
	v_add3_u32 v3, 16, v3, v115
	v_add_f32_e32 v6, v6, v8
	v_add_f32_e32 v8, v32, v33
	v_add_f32_e32 v30, v30, v31
	v_add_f32_e32 v28, v28, v29
	v_add_f32_e32 v26, v26, v27
	v_add_f32_e32 v24, v24, v25
	v_add_f32_e32 v22, v22, v23
	v_add_f32_e32 v20, v20, v21
	v_add_f32_e32 v18, v18, v19
	v_add_f32_e32 v16, v16, v17
	v_add_f32_e32 v14, v14, v15
	v_add_f32_e32 v12, v12, v13
	v_add_f32_e32 v10, v10, v11
	v_add_f32_e32 v7, v7, v9
	ds_write2_b32 v3, v2, v4 offset1:2
	ds_write2_b32 v3, v7, v10 offset0:4 offset1:6
	ds_write2_b32 v3, v12, v14 offset0:8 offset1:10
	ds_write2_b32 v3, v16, v18 offset0:12 offset1:14
	ds_write2_b32 v3, v20, v22 offset0:16 offset1:18
	ds_write2_b32 v3, v24, v26 offset0:20 offset1:22
	ds_write2_b32 v3, v28, v30 offset0:24 offset1:26
	ds_write2_b32 v3, v8, v6 offset0:28 offset1:30
